# s_setprio 3 for the latency-critical few-wave RWKV stages (wave-0 cumsum, waves 0-3 forward substitution) so the co-resident helper waves 4-7 only fill their issue gaps
# speedup vs baseline: 1.0070x; 1.0070x over previous
; __device__ __forceinline__ void rwkv_chain(LAS unsigned char* lds, int cid, const bf16_t* P0, const float* mu, const float* w0, const float* w2, const float* a0, const float* a2, ...
;     ...
;         { RW_IDS if (tid < 64) { float lw[32];
; #pragma unroll
;             for (int s = 0; s < 32; ++s) lw[s] = wS[(dir ? 31 - s : s) * 64 + tid];
; #pragma unroll
;             for (int s = 1; s < 32; ++s) lw[s] += lw[s - 1];
; #pragma unroll
;             for (int s = 0; s < 32; ++s) wS[(dir ? 31 - s : s) * 64 + tid] = lw[s]; } }
.LBB0_514:
	s_or_b64 exec, exec, s[12:13]
	v_mov_b32_e32 v8, v200
	s_waitcnt lgkmcnt(0)
	s_barrier
	s_nop 0
	v_cmp_gt_i32_e32 vcc, 64, v8
	s_and_saveexec_b64 s[12:13], vcc
	s_cbranch_execz .LBB0_516
	v_lshl_add_u32 v8, v8, 2, 0
	s_setprio 3
	s_and_b64 vcc, exec, s[10:11]
	s_cbranch_vccnz .Lrw_cum_rev
	ds_read_b32 v9, v8 offset:24576
	ds_read_b32 v17, v8 offset:24832
	ds_read_b32 v18, v8 offset:25088
	ds_read_b32 v19, v8 offset:25344
	ds_read_b32 v20, v8 offset:25600
	ds_read_b32 v21, v8 offset:25856
	ds_read_b32 v22, v8 offset:26112
	ds_read_b32 v23, v8 offset:26368
	ds_read_b32 v32, v8 offset:26624
	ds_read_b32 v33, v8 offset:26880
	ds_read_b32 v34, v8 offset:27136
	ds_read_b32 v35, v8 offset:27392
	ds_read_b32 v39, v8 offset:27648
	ds_read_b32 v114, v8 offset:27904
	ds_read_b32 v115, v8 offset:28160
	ds_read_b32 v116, v8 offset:28416
	ds_read_b32 v125, v8 offset:28672
	ds_read_b32 v126, v8 offset:28928
	ds_read_b32 v127, v8 offset:29184
	ds_read_b32 v128, v8 offset:29440
	ds_read_b32 v129, v8 offset:29696
	ds_read_b32 v130, v8 offset:29952
	ds_read_b32 v131, v8 offset:30208
	ds_read_b32 v132, v8 offset:30464
	ds_read_b32 v140, v8 offset:30720
	ds_read_b32 v141, v8 offset:30976
	ds_read_b32 v142, v8 offset:31232
	ds_read_b32 v143, v8 offset:31488
	ds_read_b32 v144, v8 offset:31744
	ds_read_b32 v145, v8 offset:32000
	ds_read_b32 v146, v8 offset:32256
	ds_read_b32 v147, v8 offset:32512
	s_waitcnt lgkmcnt(15)
	v_add_f32_e32 v17, v9, v17
	v_add_f32_e32 v18, v17, v18
	v_add_f32_e32 v19, v18, v19
	v_add_f32_e32 v20, v19, v20
	v_add_f32_e32 v21, v20, v21
	v_add_f32_e32 v22, v21, v22
	v_add_f32_e32 v23, v22, v23
	v_add_f32_e32 v32, v23, v32
	v_add_f32_e32 v33, v32, v33
	v_add_f32_e32 v34, v33, v34
	v_add_f32_e32 v35, v34, v35
	v_add_f32_e32 v39, v35, v39
	v_add_f32_e32 v114, v39, v114
	v_add_f32_e32 v115, v114, v115
	v_add_f32_e32 v116, v115, v116
	v_add_f32_e32 v125, v116, v125
	s_waitcnt lgkmcnt(14)
	v_add_f32_e32 v126, v125, v126
	s_waitcnt lgkmcnt(13)
	v_add_f32_e32 v127, v126, v127
	s_waitcnt lgkmcnt(12)
	v_add_f32_e32 v128, v127, v128
	s_waitcnt lgkmcnt(11)
	v_add_f32_e32 v129, v128, v129
	s_waitcnt lgkmcnt(10)
	v_add_f32_e32 v130, v129, v130
	s_waitcnt lgkmcnt(9)
	v_add_f32_e32 v131, v130, v131
	s_waitcnt lgkmcnt(8)
	v_add_f32_e32 v132, v131, v132
	s_waitcnt lgkmcnt(7)
	v_add_f32_e32 v140, v132, v140
	s_waitcnt lgkmcnt(6)
	v_add_f32_e32 v141, v140, v141
	s_waitcnt lgkmcnt(5)
	v_add_f32_e32 v142, v141, v142
	s_waitcnt lgkmcnt(4)
	v_add_f32_e32 v143, v142, v143
	s_waitcnt lgkmcnt(3)
	v_add_f32_e32 v144, v143, v144
	s_waitcnt lgkmcnt(2)
	v_add_f32_e32 v145, v144, v145
	s_waitcnt lgkmcnt(1)
	v_add_f32_e32 v146, v145, v146
	s_waitcnt lgkmcnt(0)
	v_add_f32_e32 v147, v146, v147
	ds_write_b32 v8, v17 offset:24832
	ds_write_b32 v8, v18 offset:25088
	ds_write_b32 v8, v19 offset:25344
	ds_write_b32 v8, v20 offset:25600
	ds_write_b32 v8, v21 offset:25856
	ds_write_b32 v8, v22 offset:26112
	ds_write_b32 v8, v23 offset:26368
	ds_write_b32 v8, v32 offset:26624
	ds_write_b32 v8, v33 offset:26880
	ds_write_b32 v8, v34 offset:27136
	ds_write_b32 v8, v35 offset:27392
	ds_write_b32 v8, v39 offset:27648
	ds_write_b32 v8, v114 offset:27904
	ds_write_b32 v8, v115 offset:28160
	ds_write_b32 v8, v116 offset:28416
	ds_write_b32 v8, v125 offset:28672
	ds_write_b32 v8, v126 offset:28928
	ds_write_b32 v8, v127 offset:29184
	ds_write_b32 v8, v128 offset:29440
	ds_write_b32 v8, v129 offset:29696
	ds_write_b32 v8, v130 offset:29952
	ds_write_b32 v8, v131 offset:30208
	ds_write_b32 v8, v132 offset:30464
	ds_write_b32 v8, v140 offset:30720
	ds_write_b32 v8, v141 offset:30976
	ds_write_b32 v8, v142 offset:31232
	ds_write_b32 v8, v143 offset:31488
	ds_write_b32 v8, v144 offset:31744
	ds_write_b32 v8, v145 offset:32000
	ds_write_b32 v8, v146 offset:32256
	ds_write_b32 v8, v147 offset:32512
	s_branch .LBB0_516

; __device__ __forceinline__ void rwkv_chain(LAS unsigned char* lds, int cid, const bf16_t* P0, const float* mu, const float* w0, const float* w2, const float* a0, const float* a2, ...
;     ...
;         if (cc + 1 < 128) { RW_IDS const int t0n = dir ? (126 - cc) * 32 : (cc + 1) * 32; RW_ISSUE(t0n); }
.LBB0_516:
	s_or_b64 exec, exec, s[12:13]
	s_setprio 0
	v_readfirstlane_b32 s50, v200
	s_cmpk_lt_u32 s50, 0x100
	s_cbranch_scc1 .Lrw_pf2_done
	s_cmpk_eq_i32 s46, 0xfe0
	s_cbranch_scc1 .Lrw_pf2_done
	s_add_i32 s7, s46, 32
	s_and_b64 vcc, s[10:11], exec
	s_cselect_b32 s7, s6, s7
	s_cmp_eq_u32 s7, 0
	s_cbranch_scc1 .Lrw_pf2_done
	s_cmpk_eq_i32 s7, 0xfe0
	s_cbranch_scc1 .Lrw_pf2_done
	s_mul_i32 s14, s7, 0xe00
	s_ashr_i32 s15, s14, 31
	s_lshl_b64 s[14:15], s[14:15], 1
	s_add_u32 s16, s88, s14
	s_addc_u32 s17, s89, s15
	v_lshl_add_u64 v[8:9], s[16:17], 0, v[40:41]
	v_mov_b32_e32 v14, v200
	v_lshl_add_u64 v[10:11], v[8:9], 0, s[24:25]
	s_mov_b32 s52, 0xffffe400
	s_mov_b32 s53, -1
	s_mov_b64 s[50:51], 0x1c00
	s_mov_b64 s[54:55], 0x2000
	s_mov_b32 s48, 0xfffe4000
	s_mov_b32 s49, -1
	global_load_dwordx2 v[52:53], v[10:11], off
	global_load_dwordx2 v[58:59], v[10:11], off offset:1024
	global_load_dwordx2 v[64:65], v[10:11], off offset:2048
	global_load_dwordx2 v[70:71], v[8:9], off offset:3072
	global_load_dwordx2 v[76:77], v[8:9], off offset:3200
	v_lshl_add_u64 v[12:13], v[10:11], 0, s[52:53]
	v_lshl_add_u64 v[16:17], v[10:11], 0, s[50:51]
	v_lshl_add_u64 v[18:19], v[8:9], 0, s[54:55]
	global_load_dwordx2 v[56:57], v[12:13], off
	global_load_dwordx2 v[60:61], v[12:13], off offset:1024
	global_load_dwordx2 v[66:67], v[12:13], off offset:2048
	global_load_dwordx2 v[72:73], v[8:9], off offset:-4096
	global_load_dwordx2 v[78:79], v[8:9], off offset:-3968
	global_load_dwordx2 v[54:55], v[16:17], off
	global_load_dwordx2 v[62:63], v[16:17], off offset:1024
	global_load_dwordx2 v[68:69], v[16:17], off offset:2048
	global_load_dwordx2 v[74:75], v[18:19], off offset:2048
	global_load_dwordx2 v[80:81], v[18:19], off offset:2176
	v_lshl_add_u64 v[20:21], v[8:9], 0, s[48:49]
	v_lshl_add_u64 v[22:23], v[10:11], 0, s[48:49]
	global_load_dwordx2 v[148:149], v[22:23], off
	global_load_dwordx2 v[154:155], v[22:23], off offset:1024
	global_load_dwordx2 v[160:161], v[22:23], off offset:2048
	global_load_dwordx2 v[166:167], v[20:21], off offset:3072
	global_load_dwordx2 v[172:173], v[20:21], off offset:3200
	v_lshl_add_u64 v[12:13], v[22:23], 0, s[52:53]
	v_lshl_add_u64 v[16:17], v[22:23], 0, s[50:51]
	v_lshl_add_u64 v[18:19], v[20:21], 0, s[54:55]
	global_load_dwordx2 v[152:153], v[12:13], off
	global_load_dwordx2 v[156:157], v[12:13], off offset:1024
	global_load_dwordx2 v[162:163], v[12:13], off offset:2048
	global_load_dwordx2 v[168:169], v[20:21], off offset:-4096
	global_load_dwordx2 v[174:175], v[20:21], off offset:-3968
	global_load_dwordx2 v[150:151], v[16:17], off
	global_load_dwordx2 v[158:159], v[16:17], off offset:1024
	global_load_dwordx2 v[164:165], v[16:17], off offset:2048
	global_load_dwordx2 v[170:171], v[18:19], off offset:2048
	global_load_dwordx2 v[176:177], v[18:19], off offset:2176
	s_and_b64 vcc, exec, s[36:37]
	s_cbranch_vccz .Lrw_pf2_done
	v_and_b32_e32 v12, 15, v14
	v_mul_u32_u24_e32 v12, 6, v12
	v_sub_co_u32_e32 v16, vcc, v8, v12
	v_mov_b32_e32 v13, 0
	s_nop 0
	v_subb_co_u32_e32 v17, vcc, v9, v13, vcc
	v_lshl_add_u64 v[16:17], s[38:39], 1, v[16:17]
	v_lshl_add_u64 v[18:19], v[16:17], 0, s[54:55]
	global_load_ushort v47, v[16:17], off offset:3328
	global_load_ushort v51, v[16:17], off offset:-3840
	global_load_ushort v49, v[18:19], off offset:2304
	v_lshl_add_u64 v[16:17], v[16:17], 0, s[48:49]
	v_lshl_add_u64 v[18:19], v[18:19], 0, s[48:49]
	global_load_ushort v178, v[16:17], off offset:3328
	global_load_ushort v179, v[16:17], off offset:-3840
	global_load_ushort v180, v[18:19], off offset:2304

; #define LAS __attribute__((address_space(3)))
; template <int CTRL> __device__ __forceinline__ float dppf(float x) { return __builtin_bit_cast(float, __builtin_amdgcn_mov_dpp(__builtin_bit_cast(int, x), CTRL, 0xf, 0xf, true)); }
; __device__ __forceinline__ f32x4 mfma16(bf16x8 bfrag, bf16x8 afrag, f32x4 acc) { return __builtin_amdgcn_mfma_f32_16x16x32_bf16(bfrag, afrag, acc, 0, 0, 0); }
; __device__ __forceinline__ void rwkv_chain(LAS unsigned char* lds, int cid, const bf16_t* P0, const float* mu, const float* w0, const float* w2, const float* a0, const float* a2, ...
;     ...
;         { RW_IDS f32x4 wacc = (f32x4){0.f, 0.f, 0.f, 0.f};
; #pragma unroll
;           for (int ks = 0; ks < 2; ++ks) { const bf16x8 sf = ldsfrag(S0b, 72, vt * 16, ks * 32, fr, fq);
;               wacc = mfma16(ldsfrag(At, 72, tt2 * 16, ks * 32, fr, fq), sf, wacc); oacc = mfma16(ldsfrag(Rt, 72, tt2 * 16, ks * 32, fr, fq), sf, oacc); }
;           const bf16x8 vf = ldsfrag(VT, 40, vt * 16, 0, fr, fq);
;           wacc = mfma16(ldsfrag(NakT, 40, tt2 * 16, 0, fr, fq), vf, wacc); oacc = mfma16(ldsfrag(MkrT, 40, tt2 * 16, 0, fr, fq), vf, oacc);
; #pragma unroll
;           for (int n2 = 0; n2 < 2; ++n2) st[n2] = mfma16(ldsfrag(KtT, 40, (tt2 * 2 + n2) * 16, 0, fr, fq), vf, st[n2]);
; #pragma unroll
;           for (int e = 0; e < 4; ++e) WS[(tt2 * 16 + fq * 4 + e) * 64 + vt * 16 + fr] = wacc[e]; }
;         __syncthreads();
;         { RW_IDS if (wid < 4) { const int v = wid * 16 + (lane >> 2), p = lane & 3; const LAS float* NTp = NT4 + p * 384; float u[8];
; #pragma unroll
;             for (int j = 0; j < 8; ++j) u[j] = 0.f;
; #pragma unroll
;             for (int t = 0; t < 32; ++t) { float q0 = (p == 0) ? WS[t * 64 + v] : 0.f, q1 = 0.f;
; #pragma unroll
;                 for (int j4 = 0; j4 < ((t + 3) / 4 + 3) / 4; ++j4) { const f32x4 nv = *(const LAS f32x4*)(NTp + t * 12 + j4 * 4);
;                     q0 += u[j4 * 4] * nv[0]; q1 += u[j4 * 4 + 1] * nv[1]; q0 += u[j4 * 4 + 2] * nv[2]; q1 += u[j4 * 4 + 3] * nv[3]; }
;                 float q = q0 + q1; q += dppf<0xB1>(q); q += dppf<0x4E>(q);
;                 u[t >> 2] = ((t & 3) == p) ? q : u[t >> 2]; asm volatile("" ::: "memory"); }
.LBB0_534:
	v_mov_b32_e32 v8, v200
	s_waitcnt lgkmcnt(0)
	s_barrier
	s_add_i32 s14, 0, 0x1d800
	v_readfirstlane_b32 s7, v8
	s_bfe_u32 s12, s7, 0x10006
	s_ashr_i32 s7, s7, 3
	v_and_b32_e32 v39, 15, v8
	v_bfe_u32 v118, v8, 4, 2
	v_bfi_b32 v8, -16, s7, v8
	v_mul_lo_u32 v28, v8, s76
	v_mul_lo_u32 v13, v8, s83
	v_lshl_or_b32 v8, s12, 5, v39
	v_lshlrev_b32_e32 v114, 4, v118
	v_lshl_or_b32 v12, s12, 4, v39
	v_mul_u32_u24_e32 v8, 0x50, v8
	v_mul_u32_u24_e32 v9, 0x48, v12
	v_add3_u32 v14, s14, v114, v8
	v_lshlrev_b32_e32 v115, 1, v9
	ds_read_b128 v[8:11], v14
	s_add_i32 s13, 0, 0x1ec00
	v_mul_u32_u24_e32 v17, 40, v12
	v_add3_u32 v16, s13, v13, v114
	s_add_i32 s13, 0, 0x23c00
	v_lshlrev_b32_e32 v24, 1, v17
	v_add3_u32 v20, s13, v24, v114
	ds_read_b128 v[12:15], v14 offset:1280
	ds_read_b128 v[16:19], v16
	ds_read_b128 v[20:23], v20
	s_add_i32 s13, 0, 0x25000
	v_add3_u32 v29, s79, v115, v114
	v_add3_u32 v24, s13, v24, v114
	ds_read_b128 v[24:27], v24
	s_waitcnt lgkmcnt(2)
	v_mfma_f32_16x16x32_bf16 v[0:3], v[8:11], v[16:19], v[0:3]
	ds_read_b128 v[8:11], v29
	v_add3_u32 v32, s85, v28, v114
	ds_read_b128 v[28:31], v29 offset:64
	v_mfma_f32_16x16x32_bf16 v[4:7], v[12:15], v[16:19], v[4:7]
	ds_read_b128 v[12:15], v32
	ds_read_b128 v[32:35], v32 offset:64
	v_add3_u32 v114, s82, v115, v114
	s_and_b32 s7, s7, -16
	s_waitcnt lgkmcnt(1)
	v_mfma_f32_16x16x32_bf16 v[8:11], v[8:11], v[12:15], 0
	s_lshl_b32 s7, s7, 2
	s_add_i32 s7, s7, 0
	s_waitcnt lgkmcnt(0)
	v_mfma_f32_16x16x32_bf16 v[8:11], v[28:31], v[32:35], v[8:11]
	ds_read_b128 v[28:31], v114
	ds_read_b128 v[114:117], v114 offset:64
	v_mfma_f32_16x16x32_bf16 v[8:11], v[20:23], v[16:19], v[8:11]
	s_mul_i32 s7, s7, 36
	v_mul_u32_u24_e32 v20, 0x90, v39
	v_lshl_add_u32 v21, v118, 4, s7
	s_lshl_b32 s7, s12, 6
	s_waitcnt lgkmcnt(1)
	v_mfma_f32_16x16x32_bf16 v[12:15], v[28:31], v[12:15], 0
	v_add3_u32 v20, v20, v21, s7
	s_nop 1
	v_mul_f32_e32 v8, 0x3e800000, v8
	v_mul_f32_e32 v9, 0x3e800000, v9
	v_mul_f32_e32 v10, 0x3e800000, v10
	v_mul_f32_e32 v11, 0x3e800000, v11
	ds_write_b128 v20, v[8:11] offset:49152
	s_waitcnt lgkmcnt(0)
	v_mfma_f32_16x16x32_bf16 v[8:11], v[114:117], v[32:35], v[12:15]
	s_barrier
	s_nop 1
	v_mov_b32_e32 v12, v200
	v_mfma_f32_16x16x32_bf16 v[8:11], v[24:27], v[16:19], v[8:11]
	s_nop 0
	v_readfirstlane_b32 s7, v12
	s_ashr_i32 s7, s7, 6
	s_cmp_gt_i32 s7, 3
	s_cbranch_scc1 .Lrw_early_s0
	s_setprio 3
	v_bfe_u32 v13, v12, 2, 4
	v_and_b32_e32 v14, 3, v12
	v_lshl_or_b32 v13, s7, 4, v13
	v_cmp_eq_u32_e32 vcc, 0, v14
	v_cmp_eq_u32_e64 s[14:15], 1, v14
	v_cmp_eq_u32_e64 s[12:13], 2, v14
	v_cmp_eq_u32_e64 s[16:17], 3, v14
	v_mul_u32_u24_e32 v12, 0x90, v13
	s_movk_i32 s7, 0x410
	v_mov_b32_e32 v15, s84
	v_mul_lo_u32 v28, v13, s83
	v_mad_u32_u24 v15, v14, s7, v15
	v_lshl_add_u32 v28, v14, 1, v28
	ds_read_b128 v[162:165], v12 offset:49152
	ds_read_b128 v[166:169], v12 offset:49168
	ds_read_b128 v[170:173], v12 offset:49184
	ds_read_b128 v[174:177], v12 offset:49200
	ds_read_b128 v[178:181], v12 offset:49216
	ds_read_b128 v[182:185], v12 offset:49232
	ds_read_b128 v[186:189], v12 offset:49248
	ds_read_b128 v[190:193], v12 offset:49264
	ds_read_b32 v122, v15 offset:32
	ds_read_b32 v130, v15 offset:64
	ds_read_b32 v138, v15 offset:96
	ds_read_b32 v146, v15 offset:128
	ds_read_b64 v[154:155], v15 offset:160
	s_waitcnt lgkmcnt(12)
	v_mul_f32_e32 v162, 4.0, v162
	v_cndmask_b32_e32 v16, 0, v162, vcc
	ds_read_b64 v[114:115], v15 offset:192
	s_waitcnt lgkmcnt(5)
	v_fmac_f32_e32 v163, v16, v122
	ds_read_b64 v[122:123], v15 offset:224
	s_nop 0
	v_add_f32_dpp v163, v163, v163 quad_perm:[1,0,3,2] row_mask:0xf bank_mask:0xf bound_ctrl:1
	s_waitcnt lgkmcnt(4)
	s_nop 0
	v_add_f32_dpp v163, v163, v163 quad_perm:[2,3,0,1] row_mask:0xf bank_mask:0xf bound_ctrl:1
	v_cndmask_b32_e64 v16, v16, v163, s[14:15]
	v_fmac_f32_e32 v164, v16, v130
	ds_read_b64 v[130:131], v15 offset:256
	s_nop 0
	v_add_f32_dpp v164, v164, v164 quad_perm:[1,0,3,2] row_mask:0xf bank_mask:0xf bound_ctrl:1
	s_nop 1
	v_add_f32_dpp v164, v164, v164 quad_perm:[2,3,0,1] row_mask:0xf bank_mask:0xf bound_ctrl:1
	v_cndmask_b32_e64 v16, v16, v164, s[12:13]
	v_fmac_f32_e32 v165, v16, v138
	ds_read_b128 v[138:141], v15 offset:288
	s_nop 0
	v_add_f32_dpp v165, v165, v165 quad_perm:[1,0,3,2] row_mask:0xf bank_mask:0xf bound_ctrl:1
	s_waitcnt lgkmcnt(4)
	s_nop 0
	v_add_f32_dpp v165, v165, v165 quad_perm:[2,3,0,1] row_mask:0xf bank_mask:0xf bound_ctrl:1
	v_cndmask_b32_e64 v16, v16, v165, s[16:17]
	v_fmac_f32_e32 v166, v16, v146
	ds_read_b128 v[146:149], v15 offset:320
	s_nop 0
	v_add_f32_dpp v166, v166, v166 quad_perm:[1,0,3,2] row_mask:0xf bank_mask:0xf bound_ctrl:1
	v_fmac_f32_e32 v167, v16, v154
	s_nop 0
	v_add_f32_dpp v166, v166, v166 quad_perm:[2,3,0,1] row_mask:0xf bank_mask:0xf bound_ctrl:1
	v_cndmask_b32_e32 v17, 0, v166, vcc
	v_fmac_f32_e32 v167, v17, v155
	ds_read_b128 v[154:157], v15 offset:352
	s_nop 0
	v_add_f32_dpp v167, v167, v167 quad_perm:[1,0,3,2] row_mask:0xf bank_mask:0xf bound_ctrl:1
	s_waitcnt lgkmcnt(4)
	s_nop 0
	v_add_f32_dpp v167, v167, v167 quad_perm:[2,3,0,1] row_mask:0xf bank_mask:0xf bound_ctrl:1
	v_fmac_f32_e32 v168, v16, v114
	v_cndmask_b32_e64 v17, v17, v167, s[14:15]
	v_fmac_f32_e32 v168, v17, v115
	ds_read_b128 v[114:117], v15 offset:384
	s_nop 0
	v_add_f32_dpp v168, v168, v168 quad_perm:[1,0,3,2] row_mask:0xf bank_mask:0xf bound_ctrl:1
	v_fmac_f32_e32 v169, v16, v122
	s_nop 0
	v_add_f32_dpp v168, v168, v168 quad_perm:[2,3,0,1] row_mask:0xf bank_mask:0xf bound_ctrl:1
	v_cndmask_b32_e64 v17, v17, v168, s[12:13]
	v_fmac_f32_e32 v169, v17, v123
	ds_read_b128 v[122:125], v15 offset:416
	s_nop 0
	v_add_f32_dpp v169, v169, v169 quad_perm:[1,0,3,2] row_mask:0xf bank_mask:0xf bound_ctrl:1
	s_waitcnt lgkmcnt(4)
; #define LAS __attribute__((address_space(3)))
; template <int CTRL> __device__ __forceinline__ float dppf(float x) { return __builtin_bit_cast(float, __builtin_amdgcn_mov_dpp(__builtin_bit_cast(int, x), CTRL, 0xf, 0xf, true)); }
; __device__ __forceinline__ void rwkv_chain(LAS unsigned char* lds, int cid, const bf16_t* P0, const float* mu, const float* w0, const float* w2, const float* a0, const float* a2, ...
;     ...
;             for (int t = 0; t < 32; ++t) { float q0 = (p == 0) ? WS[t * 64 + v] : 0.f, q1 = 0.f;
; #pragma unroll
;                 for (int j4 = 0; j4 < ((t + 3) / 4 + 3) / 4; ++j4) { const f32x4 nv = *(const LAS f32x4*)(NTp + t * 12 + j4 * 4);
;                     q0 += u[j4 * 4] * nv[0]; q1 += u[j4 * 4 + 1] * nv[1]; q0 += u[j4 * 4 + 2] * nv[2]; q1 += u[j4 * 4 + 3] * nv[3]; }
;                 float q = q0 + q1; q += dppf<0xB1>(q); q += dppf<0x4E>(q);
;                 u[t >> 2] = ((t & 3) == p) ? q : u[t >> 2]; asm volatile("" ::: "memory"); }
	s_nop 0
	v_add_f32_dpp v169, v169, v169 quad_perm:[2,3,0,1] row_mask:0xf bank_mask:0xf bound_ctrl:1
	v_fmac_f32_e32 v170, v16, v130
	v_cndmask_b32_e64 v17, v17, v169, s[16:17]
	v_fmac_f32_e32 v170, v17, v131
	ds_read_b128 v[130:133], v15 offset:448
	s_nop 0
	v_add_f32_dpp v170, v170, v170 quad_perm:[1,0,3,2] row_mask:0xf bank_mask:0xf bound_ctrl:1
	v_fmac_f32_e32 v171, v16, v138
	s_nop 0
	v_add_f32_dpp v170, v170, v170 quad_perm:[2,3,0,1] row_mask:0xf bank_mask:0xf bound_ctrl:1
	v_fmac_f32_e32 v171, v17, v139
	v_cndmask_b32_e32 v18, 0, v170, vcc
	v_fmac_f32_e32 v171, v18, v140
	ds_read_b128 v[138:141], v15 offset:480
	s_waitcnt lgkmcnt(4)
	v_add_f32_dpp v171, v171, v171 quad_perm:[1,0,3,2] row_mask:0xf bank_mask:0xf bound_ctrl:1
	v_fmac_f32_e32 v172, v16, v146
	s_nop 0
	v_add_f32_dpp v171, v171, v171 quad_perm:[2,3,0,1] row_mask:0xf bank_mask:0xf bound_ctrl:1
	v_fmac_f32_e32 v172, v17, v147
	v_cndmask_b32_e64 v18, v18, v171, s[14:15]
	v_fmac_f32_e32 v172, v18, v148
	ds_read_b128 v[146:149], v15 offset:512
	s_nop 0
	v_add_f32_dpp v172, v172, v172 quad_perm:[1,0,3,2] row_mask:0xf bank_mask:0xf bound_ctrl:1
	v_fmac_f32_e32 v173, v16, v154
	s_nop 0
	v_add_f32_dpp v172, v172, v172 quad_perm:[2,3,0,1] row_mask:0xf bank_mask:0xf bound_ctrl:1
	v_fmac_f32_e32 v173, v17, v155
	v_cndmask_b32_e64 v18, v18, v172, s[12:13]
	v_fmac_f32_e32 v173, v18, v156
	ds_read_b128 v[154:157], v15 offset:544
	ds_read_b32 v158, v15 offset:560
	v_add_f32_dpp v173, v173, v173 quad_perm:[1,0,3,2] row_mask:0xf bank_mask:0xf bound_ctrl:1
	s_waitcnt lgkmcnt(5)
	v_fmac_f32_e32 v174, v16, v114
	v_add_f32_dpp v173, v173, v173 quad_perm:[2,3,0,1] row_mask:0xf bank_mask:0xf bound_ctrl:1
	v_fmac_f32_e32 v174, v17, v115
	v_cndmask_b32_e64 v18, v18, v173, s[16:17]
	v_fmac_f32_e32 v174, v18, v116
	ds_read_b128 v[114:117], v15 offset:576
	ds_read_b32 v118, v15 offset:592
	v_add_f32_dpp v174, v174, v174 quad_perm:[1,0,3,2] row_mask:0xf bank_mask:0xf bound_ctrl:1
	v_fmac_f32_e32 v175, v16, v122
	v_fmac_f32_e32 v175, v17, v123
	v_add_f32_dpp v174, v174, v174 quad_perm:[2,3,0,1] row_mask:0xf bank_mask:0xf bound_ctrl:1
	v_fmac_f32_e32 v175, v18, v124
	v_cndmask_b32_e32 v19, 0, v174, vcc
	v_fmac_f32_e32 v175, v19, v125
	ds_read_b128 v[122:125], v15 offset:608
	ds_read_b32 v126, v15 offset:624
	v_add_f32_dpp v175, v175, v175 quad_perm:[1,0,3,2] row_mask:0xf bank_mask:0xf bound_ctrl:1
	s_waitcnt lgkmcnt(7)
	v_fmac_f32_e32 v176, v16, v130
	v_add_f32_dpp v175, v175, v175 quad_perm:[2,3,0,1] row_mask:0xf bank_mask:0xf bound_ctrl:1
	v_fmac_f32_e32 v176, v17, v131
	v_fmac_f32_e32 v176, v18, v132
	v_cndmask_b32_e64 v19, v19, v175, s[14:15]
	v_fmac_f32_e32 v176, v19, v133
	ds_read_b128 v[130:133], v15 offset:640
	ds_read_b32 v134, v15 offset:656
	v_add_f32_dpp v176, v176, v176 quad_perm:[1,0,3,2] row_mask:0xf bank_mask:0xf bound_ctrl:1
	v_fmac_f32_e32 v177, v16, v138
	v_fmac_f32_e32 v177, v17, v139
	v_add_f32_dpp v176, v176, v176 quad_perm:[2,3,0,1] row_mask:0xf bank_mask:0xf bound_ctrl:1
	v_fmac_f32_e32 v177, v18, v140
	v_cndmask_b32_e64 v19, v19, v176, s[12:13]
	v_fmac_f32_e32 v177, v19, v141
	ds_read_b128 v[138:141], v15 offset:672
	ds_read_b64 v[142:143], v15 offset:688
	v_add_f32_dpp v177, v177, v177 quad_perm:[1,0,3,2] row_mask:0xf bank_mask:0xf bound_ctrl:1
	s_waitcnt lgkmcnt(8)
	v_fmac_f32_e32 v178, v16, v146
	v_add_f32_dpp v177, v177, v177 quad_perm:[2,3,0,1] row_mask:0xf bank_mask:0xf bound_ctrl:1
	v_fmac_f32_e32 v178, v17, v147
	v_fmac_f32_e32 v178, v18, v148
	v_cndmask_b32_e64 v19, v19, v177, s[16:17]
	v_fmac_f32_e32 v178, v19, v149
	ds_read_b128 v[146:149], v15 offset:704
	ds_read_b64 v[150:151], v15 offset:720
	v_add_f32_dpp v178, v178, v178 quad_perm:[1,0,3,2] row_mask:0xf bank_mask:0xf bound_ctrl:1
	v_pk_mul_f32 v[26:27], v[16:17], v[154:155]
	v_pk_fma_f32 v[26:27], v[18:19], v[156:157], v[26:27]
	v_add_f32_dpp v178, v178, v178 quad_perm:[2,3,0,1] row_mask:0xf bank_mask:0xf bound_ctrl:1
	v_add_f32_e32 v26, v26, v27
	v_add_f32_e32 v179, v179, v26
	v_cndmask_b32_e32 v20, 0, v178, vcc
	v_fmac_f32_e32 v179, v20, v158
	ds_read_b128 v[154:157], v15 offset:736
	ds_read_b64 v[158:159], v15 offset:752
	s_waitcnt lgkmcnt(8)
	v_add_f32_dpp v179, v179, v179 quad_perm:[1,0,3,2] row_mask:0xf bank_mask:0xf bound_ctrl:1
	v_pk_mul_f32 v[24:25], v[16:17], v[114:115]
	v_pk_fma_f32 v[24:25], v[18:19], v[116:117], v[24:25]
	v_add_f32_dpp v179, v179, v179 quad_perm:[2,3,0,1] row_mask:0xf bank_mask:0xf bound_ctrl:1
	v_add_f32_e32 v24, v24, v25
	v_add_f32_e32 v180, v180, v24
	v_cndmask_b32_e64 v20, v20, v179, s[14:15]
	v_fmac_f32_e32 v180, v20, v118
	ds_read_b128 v[114:117], v15 offset:768
	ds_read_b64 v[118:119], v15 offset:784
	v_add_f32_dpp v180, v180, v180 quad_perm:[1,0,3,2] row_mask:0xf bank_mask:0xf bound_ctrl:1
	v_pk_mul_f32 v[26:27], v[16:17], v[122:123]
	v_pk_fma_f32 v[26:27], v[18:19], v[124:125], v[26:27]
	v_add_f32_dpp v180, v180, v180 quad_perm:[2,3,0,1] row_mask:0xf bank_mask:0xf bound_ctrl:1
	v_add_f32_e32 v26, v26, v27
	v_add_f32_e32 v181, v181, v26
	v_cndmask_b32_e64 v20, v20, v180, s[12:13]
	v_fmac_f32_e32 v181, v20, v126
	ds_read_b128 v[122:125], v15 offset:800
	ds_read_b128 v[126:129], v15 offset:816
	s_waitcnt lgkmcnt(8)
; #define LAS __attribute__((address_space(3)))
; template <int CTRL> __device__ __forceinline__ float dppf(float x) { return __builtin_bit_cast(float, __builtin_amdgcn_mov_dpp(__builtin_bit_cast(int, x), CTRL, 0xf, 0xf, true)); }
; __device__ __forceinline__ void rwkv_chain(LAS unsigned char* lds, int cid, const bf16_t* P0, const float* mu, const float* w0, const float* w2, const float* a0, const float* a2, ...
;     ...
;             for (int t = 0; t < 32; ++t) { float q0 = (p == 0) ? WS[t * 64 + v] : 0.f, q1 = 0.f;
; #pragma unroll
;                 for (int j4 = 0; j4 < ((t + 3) / 4 + 3) / 4; ++j4) { const f32x4 nv = *(const LAS f32x4*)(NTp + t * 12 + j4 * 4);
;                     q0 += u[j4 * 4] * nv[0]; q1 += u[j4 * 4 + 1] * nv[1]; q0 += u[j4 * 4 + 2] * nv[2]; q1 += u[j4 * 4 + 3] * nv[3]; }
;                 float q = q0 + q1; q += dppf<0xB1>(q); q += dppf<0x4E>(q);
;                 u[t >> 2] = ((t & 3) == p) ? q : u[t >> 2]; asm volatile("" ::: "memory"); }
	v_add_f32_dpp v181, v181, v181 quad_perm:[1,0,3,2] row_mask:0xf bank_mask:0xf bound_ctrl:1
	v_pk_mul_f32 v[24:25], v[16:17], v[130:131]
	v_pk_fma_f32 v[24:25], v[18:19], v[132:133], v[24:25]
	v_add_f32_dpp v181, v181, v181 quad_perm:[2,3,0,1] row_mask:0xf bank_mask:0xf bound_ctrl:1
	v_add_f32_e32 v24, v24, v25
	v_add_f32_e32 v182, v182, v24
	v_cndmask_b32_e64 v20, v20, v181, s[16:17]
	v_fmac_f32_e32 v182, v20, v134
	ds_read_b128 v[130:133], v15 offset:832
	ds_read_b128 v[134:137], v15 offset:848
	v_pk_mul_f32 v[26:27], v[16:17], v[138:139]
	v_add_f32_dpp v182, v182, v182 quad_perm:[1,0,3,2] row_mask:0xf bank_mask:0xf bound_ctrl:1
	v_pk_fma_f32 v[26:27], v[18:19], v[140:141], v[26:27]
	v_fmac_f32_e32 v183, v20, v142
	v_add_f32_dpp v182, v182, v182 quad_perm:[2,3,0,1] row_mask:0xf bank_mask:0xf bound_ctrl:1
	v_add_f32_e32 v26, v26, v27
	v_add_f32_e32 v183, v183, v26
	v_cndmask_b32_e32 v21, 0, v182, vcc
	v_fmac_f32_e32 v183, v21, v143
	ds_read_b128 v[138:141], v15 offset:864
	ds_read_b128 v[142:145], v15 offset:880
	s_waitcnt lgkmcnt(8)
	v_add_f32_dpp v183, v183, v183 quad_perm:[1,0,3,2] row_mask:0xf bank_mask:0xf bound_ctrl:1
	v_pk_mul_f32 v[24:25], v[16:17], v[146:147]
	v_pk_fma_f32 v[24:25], v[18:19], v[148:149], v[24:25]
	v_fmac_f32_e32 v184, v20, v150
	v_add_f32_dpp v183, v183, v183 quad_perm:[2,3,0,1] row_mask:0xf bank_mask:0xf bound_ctrl:1
	v_add_f32_e32 v24, v24, v25
	v_add_f32_e32 v184, v184, v24
	v_cndmask_b32_e64 v21, v21, v183, s[14:15]
	v_fmac_f32_e32 v184, v21, v151
	ds_read_b128 v[146:149], v15 offset:896
	ds_read_b128 v[150:153], v15 offset:912
	v_pk_mul_f32 v[26:27], v[16:17], v[154:155]
	v_add_f32_dpp v184, v184, v184 quad_perm:[1,0,3,2] row_mask:0xf bank_mask:0xf bound_ctrl:1
	v_pk_fma_f32 v[26:27], v[18:19], v[156:157], v[26:27]
	v_fmac_f32_e32 v185, v20, v158
	v_add_f32_dpp v184, v184, v184 quad_perm:[2,3,0,1] row_mask:0xf bank_mask:0xf bound_ctrl:1
	v_add_f32_e32 v26, v26, v27
	v_add_f32_e32 v185, v185, v26
	v_cndmask_b32_e64 v21, v21, v184, s[12:13]
	v_fmac_f32_e32 v185, v21, v159
	ds_read_b128 v[154:157], v15 offset:928
	ds_read_b128 v[158:161], v15 offset:944
	s_waitcnt lgkmcnt(8)
	v_add_f32_dpp v185, v185, v185 quad_perm:[1,0,3,2] row_mask:0xf bank_mask:0xf bound_ctrl:1
	v_pk_mul_f32 v[24:25], v[16:17], v[114:115]
	v_pk_fma_f32 v[24:25], v[18:19], v[116:117], v[24:25]
	v_fmac_f32_e32 v186, v20, v118
	v_add_f32_dpp v185, v185, v185 quad_perm:[2,3,0,1] row_mask:0xf bank_mask:0xf bound_ctrl:1
	v_add_f32_e32 v24, v24, v25
	v_add_f32_e32 v186, v186, v24
	v_cndmask_b32_e64 v21, v21, v185, s[16:17]
	v_fmac_f32_e32 v186, v21, v119
	ds_read_b128 v[114:117], v15 offset:960
	ds_read_b128 v[118:121], v15 offset:976
	v_pk_mul_f32 v[26:27], v[16:17], v[122:123]
	v_add_f32_dpp v186, v186, v186 quad_perm:[1,0,3,2] row_mask:0xf bank_mask:0xf bound_ctrl:1
	v_pk_fma_f32 v[26:27], v[18:19], v[124:125], v[26:27]
	v_pk_fma_f32 v[26:27], v[20:21], v[126:127], v[26:27]
	v_add_f32_dpp v186, v186, v186 quad_perm:[2,3,0,1] row_mask:0xf bank_mask:0xf bound_ctrl:1
	v_add_f32_e32 v26, v26, v27
	v_add_f32_e32 v187, v187, v26
	v_cndmask_b32_e32 v22, 0, v186, vcc
	v_fmac_f32_e32 v187, v22, v128
	ds_read_b128 v[122:125], v15 offset:992
	ds_read_b128 v[126:129], v15 offset:1008
	s_waitcnt lgkmcnt(8)
; #define LAS __attribute__((address_space(3)))
; __device__ __forceinline__ unsigned f2bf(float f) { return pk2(f, 0.f) & 0xffffu; }
; template <int CTRL> __device__ __forceinline__ float dppf(float x) { return __builtin_bit_cast(float, __builtin_amdgcn_mov_dpp(__builtin_bit_cast(int, x), CTRL, 0xf, 0xf, true)); }
; __device__ __forceinline__ void rwkv_chain(LAS unsigned char* lds, int cid, const bf16_t* P0, const float* mu, const float* w0, const float* w2, const float* a0, const float* a2, ...
;     ...
;             for (int t = 0; t < 32; ++t) { float q0 = (p == 0) ? WS[t * 64 + v] : 0.f, q1 = 0.f;
; #pragma unroll
;                 for (int j4 = 0; j4 < ((t + 3) / 4 + 3) / 4; ++j4) { const f32x4 nv = *(const LAS f32x4*)(NTp + t * 12 + j4 * 4);
;                     q0 += u[j4 * 4] * nv[0]; q1 += u[j4 * 4 + 1] * nv[1]; q0 += u[j4 * 4 + 2] * nv[2]; q1 += u[j4 * 4 + 3] * nv[3]; }
;                 float q = q0 + q1; q += dppf<0xB1>(q); q += dppf<0x4E>(q);
;                 u[t >> 2] = ((t & 3) == p) ? q : u[t >> 2]; asm volatile("" ::: "memory"); }
; #pragma unroll
;             for (int j = 0; j < 8; ++j) Ub[v * 40 + 4 * j + p] = (bf16_t)f2bf(u[j]); } }
	v_add_f32_dpp v187, v187, v187 quad_perm:[1,0,3,2] row_mask:0xf bank_mask:0xf bound_ctrl:1
	v_pk_mul_f32 v[24:25], v[16:17], v[130:131]
	v_pk_fma_f32 v[24:25], v[18:19], v[132:133], v[24:25]
	v_pk_fma_f32 v[24:25], v[20:21], v[134:135], v[24:25]
	v_add_f32_dpp v187, v187, v187 quad_perm:[2,3,0,1] row_mask:0xf bank_mask:0xf bound_ctrl:1
	v_add_f32_e32 v24, v24, v25
	v_add_f32_e32 v188, v188, v24
	v_cndmask_b32_e64 v22, v22, v187, s[14:15]
	v_fmac_f32_e32 v188, v22, v136
	v_pk_mul_f32 v[26:27], v[16:17], v[138:139]
	v_pk_fma_f32 v[26:27], v[18:19], v[140:141], v[26:27]
	v_add_f32_dpp v188, v188, v188 quad_perm:[1,0,3,2] row_mask:0xf bank_mask:0xf bound_ctrl:1
	v_pk_fma_f32 v[26:27], v[20:21], v[142:143], v[26:27]
	v_add_f32_e32 v26, v26, v27
	v_add_f32_dpp v188, v188, v188 quad_perm:[2,3,0,1] row_mask:0xf bank_mask:0xf bound_ctrl:1
	v_add_f32_e32 v189, v189, v26
	v_cndmask_b32_e64 v22, v22, v188, s[12:13]
	v_fmac_f32_e32 v189, v22, v144
	s_waitcnt lgkmcnt(4)
	v_pk_mul_f32 v[24:25], v[16:17], v[146:147]
	v_add_f32_dpp v189, v189, v189 quad_perm:[1,0,3,2] row_mask:0xf bank_mask:0xf bound_ctrl:1
	v_pk_fma_f32 v[24:25], v[18:19], v[148:149], v[24:25]
	v_pk_fma_f32 v[24:25], v[20:21], v[150:151], v[24:25]
	v_add_f32_dpp v189, v189, v189 quad_perm:[2,3,0,1] row_mask:0xf bank_mask:0xf bound_ctrl:1
	v_add_f32_e32 v24, v24, v25
	v_add_f32_e32 v190, v190, v24
	v_cndmask_b32_e64 v22, v22, v189, s[16:17]
	v_fmac_f32_e32 v190, v22, v152
	v_pk_mul_f32 v[26:27], v[16:17], v[154:155]
	v_pk_fma_f32 v[26:27], v[18:19], v[156:157], v[26:27]
	v_add_f32_dpp v190, v190, v190 quad_perm:[1,0,3,2] row_mask:0xf bank_mask:0xf bound_ctrl:1
	v_pk_fma_f32 v[26:27], v[20:21], v[158:159], v[26:27]
	v_fmac_f32_e32 v191, v22, v160
	v_add_f32_dpp v190, v190, v190 quad_perm:[2,3,0,1] row_mask:0xf bank_mask:0xf bound_ctrl:1
	v_add_f32_e32 v26, v26, v27
	v_add_f32_e32 v191, v191, v26
	v_cndmask_b32_e32 v23, 0, v190, vcc
	v_fmac_f32_e32 v191, v23, v161
	s_waitcnt lgkmcnt(0)
	v_pk_mul_f32 v[24:25], v[16:17], v[114:115]
	v_pk_fma_f32 v[24:25], v[18:19], v[116:117], v[24:25]
	v_add_f32_dpp v191, v191, v191 quad_perm:[1,0,3,2] row_mask:0xf bank_mask:0xf bound_ctrl:1
	v_pk_fma_f32 v[24:25], v[20:21], v[118:119], v[24:25]
	v_fmac_f32_e32 v192, v22, v120
	v_add_f32_dpp v191, v191, v191 quad_perm:[2,3,0,1] row_mask:0xf bank_mask:0xf bound_ctrl:1
	v_add_f32_e32 v24, v24, v25
	v_add_f32_e32 v192, v192, v24
	v_cndmask_b32_e64 v23, v23, v191, s[14:15]
	v_fmac_f32_e32 v192, v23, v121
	v_pk_mul_f32 v[26:27], v[16:17], v[122:123]
	v_pk_fma_f32 v[26:27], v[18:19], v[124:125], v[26:27]
	v_add_f32_dpp v192, v192, v192 quad_perm:[1,0,3,2] row_mask:0xf bank_mask:0xf bound_ctrl:1
	v_pk_fma_f32 v[26:27], v[20:21], v[126:127], v[26:27]
	v_fmac_f32_e32 v193, v22, v128
	v_add_f32_dpp v192, v192, v192 quad_perm:[2,3,0,1] row_mask:0xf bank_mask:0xf bound_ctrl:1
	v_add_f32_e32 v26, v26, v27
	v_add_f32_e32 v193, v193, v26
	v_cndmask_b32_e64 v23, v23, v192, s[12:13]
	v_fmac_f32_e32 v193, v23, v129
	s_nop 1
	v_add_f32_dpp v193, v193, v193 quad_perm:[1,0,3,2] row_mask:0xf bank_mask:0xf bound_ctrl:1
	s_nop 1
	v_add_f32_dpp v193, v193, v193 quad_perm:[2,3,0,1] row_mask:0xf bank_mask:0xf bound_ctrl:1
	v_cndmask_b32_e64 v23, v23, v193, s[16:17]
	v_cvt_pk_bf16_f32 v30, v16, v16
	ds_write_b16 v28, v30 offset:58368
	v_cvt_pk_bf16_f32 v31, v17, v17
	ds_write_b16 v28, v31 offset:58376
	v_cvt_pk_bf16_f32 v30, v18, v18
	ds_write_b16 v28, v30 offset:58384
	v_cvt_pk_bf16_f32 v31, v19, v19
	ds_write_b16 v28, v31 offset:58392
	v_cvt_pk_bf16_f32 v30, v20, v20
	ds_write_b16 v28, v30 offset:58400
	v_cvt_pk_bf16_f32 v31, v21, v21
	ds_write_b16 v28, v31 offset:58408
	v_cvt_pk_bf16_f32 v30, v22, v22
	ds_write_b16 v28, v30 offset:58416
	v_cvt_pk_bf16_f32 v31, v23, v23
	ds_write_b16 v28, v31 offset:58424
	s_setprio 0
	s_branch .LBB0_488
